# v10 + rw2 consumer loop hand-scheduled: operand LDS reads first with counted waits, four S-update groups interleaved on separate accumulators, plain f32 VALU instead of packed
# speedup vs baseline: 1.0446x; 1.0033x over previous
; #define GAS __attribute__((address_space(1)))
; #define LAS __attribute__((address_space(3)))
; __device__ __forceinline__ void rw2_phase(const Ctx& c0) { const Ctx c = fresh(c0);
;     ...
;         for (int n = 0; n < 128; ++n) {
;             const LAS unsigned char* sl = ring + (n % 5) * SLOT;
;             u32x4 caf[8], cbf[8]; f32x4 cvk[4], cpl[4];
; #pragma unroll
;             for (int f = 0; f < 8; ++f) caf[f] = *(const LAS u32x4*)(sl + f * 1024 + lane * 16);
; #pragma unroll
;             for (int f = 0; f < 8; ++f) cbf[f] = *(const LAS u32x4*)(sl + 8192 + f * 1024 + lane * 16);
; #pragma unroll
;             for (int kt = 0; kt < 4; ++kt) { const u32x2 vk = *(const LAS u32x2*)(sl + 16384 + (kt * 4 + vt) * 512 + lane * 8); cvk[kt] = (f32x4){bf_lo(vk.x), bf_hi(vk.x), bf_lo(vk.y), bf_hi(vk.y)};
;                 cpl[kt] = *(const LAS f32x4*)(sl + 24 * 1024 + (16 * kt + 4 * q) * 4); }
;             u32x4 sb[2];
; #pragma unroll
;             for (int s2 = 0; s2 < 2; ++s2) { sb[s2].x = cvt_pk_bf16(S[2 * s2][0], S[2 * s2][1]); sb[s2].y = cvt_pk_bf16(S[2 * s2][2], S[2 * s2][3]); sb[s2].z = cvt_pk_bf16(S[2 * s2 + 1][0], S[2 * s2 + 1][1]); sb[s2].w = cvt_pk_bf16(S[2 * s2 + 1][2], S[2 * s2 + 1][3]);
;                 *(GAS u32x2*)(S0B + (size_t)n * 4096 + 32 * s2) = (u32x2){sb[s2].x, sb[s2].y}; *(GAS u32x2*)(S0B + (size_t)n * 4096 + 32 * s2 + 16) = (u32x2){sb[s2].z, sb[s2].w}; }
;             f32x4 X[4];
; #pragma unroll
;             for (int mt = 0; mt < 4; ++mt) { X[mt] = (f32x4){0.f, 0.f, 0.f, 0.f};
; #pragma unroll
;                 for (int s2 = 0; s2 < 2; ++s2) X[mt] = __builtin_amdgcn_mfma_f32_16x16x32_bf16(__builtin_bit_cast(bf16x8, caf[mt * 2 + s2]), __builtin_bit_cast(bf16x8, sb[s2]), X[mt], 0, 0, 0); }
;             u32x4 xb[2];
; #pragma unroll
;             for (int s2 = 0; s2 < 2; ++s2) { xb[s2].x = cvt_pk_bf16(X[2 * s2][0], X[2 * s2][1]); xb[s2].y = cvt_pk_bf16(X[2 * s2][2], X[2 * s2][3]); xb[s2].z = cvt_pk_bf16(X[2 * s2 + 1][0], X[2 * s2 + 1][1]); xb[s2].w = cvt_pk_bf16(X[2 * s2 + 1][2], X[2 * s2 + 1][3]);
;                 *(GAS u32x2*)(XTB + (size_t)n * 4096 + 32 * s2) = (u32x2){xb[s2].x, xb[s2].y}; *(GAS u32x2*)(XTB + (size_t)n * 4096 + 32 * s2 + 16) = (u32x2){xb[s2].z, xb[s2].w}; }
; #pragma unroll
;             for (int kt = 0; kt < 4; ++kt) { f32x4 a = S[kt] + cvk[kt];
; #pragma unroll
.LBB0_2424:
	s_mul_i32 s9, s1, 0xcd
	s_bfe_u32 s9, s9, 0x6000a
	s_mul_i32 s9, s9, 5
	s_sub_i32 s9, s1, s9
	s_and_b32 s9, s9, 0xff
	s_mulk_i32 s9, 0x6400
	s_addk_i32 s9, 0x400
	s_add_i32 s10, s9, s8
	v_add_u32_e32 v6, s9, v82
	v_add_u32_e32 v42, s10, v0
	v_add_u32_e32 v168, s9, v83
	ds_read2st64_b64 v[34:37], v42 offset0:32 offset1:36
	ds_read_b128 v[46:49], v168 offset:24576
	ds_read_b128 v[50:53], v6
	ds_read_b128 v[54:57], v6 offset:1024
	ds_read_b128 v[58:61], v6 offset:2048
	ds_read_b128 v[62:65], v6 offset:3072
	ds_read_b128 v[66:69], v6 offset:4096
	ds_read_b128 v[70:73], v6 offset:5120
	ds_read_b128 v[74:77], v6 offset:6144
	ds_read_b128 v[78:81], v6 offset:7168
	v_cvt_pk_bf16_f32 v118, v86, v87
	v_cvt_pk_bf16_f32 v119, v88, v89
	v_cvt_pk_bf16_f32 v120, v90, v91
	v_cvt_pk_bf16_f32 v121, v92, v93
	v_cvt_pk_bf16_f32 v122, v94, v95
	v_cvt_pk_bf16_f32 v123, v96, v97
	v_cvt_pk_bf16_f32 v124, v98, v99
	v_cvt_pk_bf16_f32 v125, v100, v101
	ds_write2_b64 v146, v[118:119], v[120:121] offset1:4
	ds_write2_b64 v146, v[122:123], v[124:125] offset0:8 offset1:12
	ds_read_b128 v[130:133], v147
	ds_read_b128 v[134:137], v147 offset:1152
	s_waitcnt lgkmcnt(10)
	v_mfma_f32_16x16x32_bf16 v[50:53], v[50:53], v[118:121], 0
	v_lshlrev_b32_e32 v108, 16, v34
	v_and_b32_e32 v109, 0xffff0000, v34
	v_mfma_f32_16x16x32_bf16 v[50:53], v[54:57], v[122:125], v[50:53]
	v_lshlrev_b32_e32 v116, 16, v35
	v_and_b32_e32 v117, 0xffff0000, v35
	s_waitcnt lgkmcnt(8)
	ds_read_b128 v[26:29], v6 offset:8192
	ds_read_b128 v[30:33], v6 offset:9216
	v_mfma_f32_16x16x32_bf16 v[54:57], v[58:61], v[118:121], 0
	v_lshlrev_b32_e32 v106, 16, v36
	v_and_b32_e32 v107, 0xffff0000, v36
	s_waitcnt lgkmcnt(8)
	v_mfma_f32_16x16x32_bf16 v[58:61], v[66:69], v[118:121], 0
	ds_read_b128 v[18:21], v6 offset:10240
	ds_read_b128 v[22:25], v6 offset:11264
	v_mfma_f32_16x16x32_bf16 v[54:57], v[62:65], v[122:125], v[54:57]
	v_lshlrev_b32_e32 v114, 16, v37
	v_and_b32_e32 v115, 0xffff0000, v37
	v_mfma_f32_16x16x32_bf16 v[58:61], v[70:73], v[122:125], v[58:61]
	s_waitcnt lgkmcnt(8)
	v_mfma_f32_16x16x32_bf16 v[62:65], v[74:77], v[118:121], 0
	ds_read_b128 v[10:13], v6 offset:12288
	ds_read_b128 v[14:17], v6 offset:13312
	v_mfma_f32_16x16x32_bf16 v[62:65], v[78:81], v[122:125], v[62:65]
	ds_read_b128 v[2:5], v6 offset:14336
	ds_read_b128 v[6:9], v6 offset:15360
	v_add_f32_e32 v152, v86, v108
	v_add_f32_e32 v153, v87, v109
	v_add_f32_e32 v154, v88, v116
	v_add_f32_e32 v155, v89, v117
	v_add_f32_e32 v156, v90, v106
	v_add_f32_e32 v157, v91, v107
	v_add_f32_e32 v158, v92, v114
	v_add_f32_e32 v159, v93, v115
	s_waitcnt lgkmcnt(8)
	ds_read2st64_b64 v[170:173], v42 offset0:40 offset1:44
	ds_read_b128 v[38:41], v168 offset:24640
	ds_read_b128 v[174:177], v168 offset:24704
	ds_read_b128 v[178:181], v168 offset:24768
	v_cvt_pk_bf16_f32 v50, v50, v51
	v_cvt_pk_bf16_f32 v51, v52, v53
	v_cvt_pk_bf16_f32 v52, v54, v55
	v_cvt_pk_bf16_f32 v53, v56, v57
	s_waitcnt lgkmcnt(3)
	v_lshlrev_b32_e32 v104, 16, v170
	v_and_b32_e32 v105, 0xffff0000, v170
	v_lshlrev_b32_e32 v112, 16, v171
	v_and_b32_e32 v113, 0xffff0000, v171
	v_add_f32_e32 v160, v94, v104
	v_add_f32_e32 v161, v95, v105
	v_add_f32_e32 v162, v96, v112
	v_add_f32_e32 v163, v97, v113
	v_mfma_f32_16x16x32_bf16 v[152:155], v[26:29], v[50:53], v[152:155]
	v_lshlrev_b32_e32 v102, 16, v172
	v_and_b32_e32 v103, 0xffff0000, v172
	v_mfma_f32_16x16x32_bf16 v[156:159], v[18:21], v[50:53], v[156:159]
	v_lshlrev_b32_e32 v110, 16, v173
	v_and_b32_e32 v111, 0xffff0000, v173
	v_mfma_f32_16x16x32_bf16 v[160:163], v[10:13], v[50:53], v[160:163]
	v_add_f32_e32 v164, v98, v102
	v_add_f32_e32 v165, v99, v103
	v_add_f32_e32 v166, v100, v110
	v_add_f32_e32 v167, v101, v111
	v_cvt_pk_bf16_f32 v54, v58, v59
	v_cvt_pk_bf16_f32 v55, v60, v61
	v_mfma_f32_16x16x32_bf16 v[164:167], v[2:5], v[50:53], v[164:167]
	v_cvt_pk_bf16_f32 v56, v62, v63
	v_cvt_pk_bf16_f32 v57, v64, v65
	s_waitcnt lgkmcnt(0)
	s_barrier
	v_mfma_f32_16x16x32_bf16 v[152:155], v[30:33], v[54:57], v[152:155]
	v_mfma_f32_16x16x32_bf16 v[156:159], v[22:25], v[54:57], v[156:159]
	v_mfma_f32_16x16x32_bf16 v[160:163], v[14:17], v[54:57], v[160:163]
	v_mfma_f32_16x16x32_bf16 v[164:167], v[6:9], v[54:57], v[164:167]
	ds_write2_b64 v146, v[50:51], v[52:53] offset1:4
	ds_write2_b64 v146, v[54:55], v[56:57] offset0:8 offset1:12
	ds_read_b128 v[138:141], v147
	ds_read_b128 v[142:145], v147 offset:1152
	global_store_dwordx4 v148, v[130:133], s[40:41]
	global_store_dwordx4 v148, v[134:137], s[40:41] offset:1024
	v_mul_f32_e32 v86, v46, v152
	v_mul_f32_e32 v87, v47, v153
	v_mul_f32_e32 v88, v48, v154
	v_mul_f32_e32 v89, v49, v155
	v_mul_f32_e32 v90, v38, v156
	v_mul_f32_e32 v91, v39, v157
	v_mul_f32_e32 v92, v40, v158
	v_mul_f32_e32 v93, v41, v159
	v_mul_f32_e32 v94, v174, v160
	v_mul_f32_e32 v95, v175, v161
	v_mul_f32_e32 v96, v176, v162
	v_mul_f32_e32 v97, v177, v163
	v_mul_f32_e32 v98, v178, v164
	v_mul_f32_e32 v99, v179, v165
	v_mul_f32_e32 v100, v180, v166
	v_mul_f32_e32 v101, v181, v167
	s_add_i32 s1, s1, 1
	s_add_u32 s6, s6, 0x2000
	s_addc_u32 s7, s7, 0
	s_waitcnt lgkmcnt(0)
	global_store_dwordx4 v148, v[138:141], s[42:43]
	global_store_dwordx4 v148, v[142:145], s[42:43] offset:1024
	v_add_u32_e32 v148, 0x2000, v148
	s_cmp_eq_u32 s6, 0x100000
	s_cbranch_scc0 .LBB0_2424
	s_mov_b64 s[6:7], 0
